# attention: rope-key tile DMA issued by waves 0-3 only (was duplicated by both wave halves)
# baseline (speedup 1.0000x reference)
; #define WAIT_BAR(N) asm volatile("s_waitcnt vmcnt(" #N ") lgkmcnt(0)\n\ts_barrier" ::: "memory")
; #define DMA_TILE(t, ks, vs) do { glds16(ksrc + (long)(t) * KVBLK * KNP, (unsigned)__builtin_amdgcn_readfirstlane(kdst + (ks) * KSLOT)); \
;         glds16(k2src + (long)(t) * KVBLK * KPP, (unsigned)__builtin_amdgcn_readfirstlane(k2dst + (ks) * KSLOT)); \
;         glds16(vsrc + (long)(t) * KVBLK * VP, (unsigned)__builtin_amdgcn_readfirstlane(vdst + (vs) * VSLOT)); } while (0)
; #define K_LOAD(ks) do { const LAS char* kp_ = kp0 + (ks) * KSLOT; \
;         _Pragma("unroll") for (int i_ = 0; i_ < 6; ++i_) { kf[2 * i_] = *(const LAS bf16x8*)(kp_ + i_ * 2048); kf[2 * i_ + 1] = *(const LAS bf16x8*)(kp_ + i_ * 2048 + 512); } SBAR(); } while (0)
; __device__ __forceinline__ void attn_unit(int b, int h, int qb, const bf16* Q, const bf16* __restrict__ Kn, const bf16* __restrict__ Kpe, const bf16* __restrict__ V, bf16* O, float* ASS, LAS char* shm) {
;     ...
;     int ks = 0, vs = 0;
;     if (wid < 4) {
;         for (int t = 0; t < NT; ++t) {
;             if (t + 1 < NT) { WAIT_BAR(3); } else { WAIT_BAR(0); }
;             K_LOAD(ks);
;             if (t + 2 < NT) DMA_TILE(t + 2, (ks == 0) ? 2 : ks - 1, (vs + 2) & 3);
;     ...
;         for (int t = 0; t < NT; ++t) {
;             if (t + 1 < NT) { WAIT_BAR(3); } else { WAIT_BAR(0); }
.Lat_u1_loop:
	s_add_i32 s4, s52, 1
	s_cmp_ge_u32 s4, s86
	s_cbranch_scc1 .Lat_u1x_lw
	s_cmp_lt_u32 s69, 4
	s_cbranch_scc0 .Lat_u1x_w2
	s_waitcnt vmcnt(3) lgkmcnt(0)
	s_branch .Lat_u1x_bar
.Lat_u1x_w2:
	s_waitcnt vmcnt(2) lgkmcnt(0)
	s_branch .Lat_u1x_bar

.Lat_u1x_bar:
	s_barrier
	s_lshr_b32 s4, s69, 1
	s_sub_u32 s4, s52, s4
	s_cmp_gt_i32 s4, s87
	s_cbranch_scc1 .Lat_u1x_noqk
	s_mul_i32 s53, s48, 0x3000
	v_add_u32_e32 v158, s53, v146
	ds_read_b128 v[196:199], v158
	ds_read_b128 v[200:203], v158 offset:512
	ds_read_b128 v[204:207], v158 offset:2048
	ds_read_b128 v[208:211], v158 offset:2560
	ds_read_b128 v[212:215], v158 offset:4096
	ds_read_b128 v[230:233], v158 offset:4608
	ds_read_b128 v[234:237], v158 offset:6144
	ds_read_b128 v[164:167], v158 offset:6656
	ds_read_b128 v[168:171], v158 offset:8192
	ds_read_b128 v[172:175], v158 offset:8704
	ds_read_b128 v[148:151], v158 offset:10240
	ds_read_b128 v[152:155], v158 offset:10752
	s_lshl_b32 s4, s50, 13
	s_add_i32 s4, s4, 0x6000
	s_and_b32 s4, s4, 0x6000
	v_add_u32_e32 v159, s4, v144
	v_mov_b32_e32 v156, 0
	v_mov_b32_e32 v157, 0
	s_waitcnt lgkmcnt(11)
	v_mfma_f32_32x32x16_bf16 v[238:253], v[196:199], v[100:103], v[104:119]
	ds_read_b64_tr_b16 v[196:197], v159 offset:36864
	ds_read_b64_tr_b16 v[198:199], v159 offset:37376
	v_exp_f32_e32 v64, v64
	v_exp_f32_e32 v65, v65
	v_add_f32_e32 v156, v156, v64
	v_add_f32_e32 v156, v156, v65
	v_cvt_pk_bf16_f32 v64, v64, v65
	s_waitcnt lgkmcnt(12)
	v_mfma_f32_32x32x16_bf16 v[180:195], v[200:203], v[100:103], v[104:119]
	ds_read_b64_tr_b16 v[200:201], v159 offset:37888
	ds_read_b64_tr_b16 v[202:203], v159 offset:38400
	v_exp_f32_e32 v66, v66
	v_exp_f32_e32 v67, v67
	v_add_f32_e32 v157, v157, v66
	v_add_f32_e32 v157, v157, v67
	v_cvt_pk_bf16_f32 v65, v66, v67
	s_waitcnt lgkmcnt(13)
	v_mfma_f32_32x32x16_bf16 v[238:253], v[204:207], v[96:99], v[238:253]
	ds_read_b64_tr_b16 v[204:205], v159 offset:38912
	ds_read_b64_tr_b16 v[206:207], v159 offset:39424
	v_exp_f32_e32 v68, v68
	v_exp_f32_e32 v69, v69
	v_add_f32_e32 v156, v156, v68
	v_add_f32_e32 v156, v156, v69
	v_cvt_pk_bf16_f32 v66, v68, v69
	s_waitcnt lgkmcnt(14)
	v_mfma_f32_32x32x16_bf16 v[180:195], v[208:211], v[96:99], v[180:195]
	ds_read_b64_tr_b16 v[208:209], v159 offset:39936
	ds_read_b64_tr_b16 v[210:211], v159 offset:40448
	v_exp_f32_e32 v70, v70
	v_exp_f32_e32 v71, v71
	v_add_f32_e32 v157, v157, v70
	v_add_f32_e32 v157, v157, v71
	v_cvt_pk_bf16_f32 v67, v70, v71
	s_waitcnt lgkmcnt(15)
	v_mfma_f32_32x32x16_bf16 v[238:253], v[212:215], v[92:95], v[238:253]
	ds_read_b64_tr_b16 v[212:213], v159 offset:40960
	ds_read_b64_tr_b16 v[214:215], v159 offset:41472
	v_exp_f32_e32 v72, v72
	v_exp_f32_e32 v73, v73
	v_add_f32_e32 v156, v156, v72
	v_add_f32_e32 v156, v156, v73
	v_cvt_pk_bf16_f32 v68, v72, v73
	s_waitcnt lgkmcnt(15)
	v_mfma_f32_32x32x16_bf16 v[180:195], v[230:233], v[92:95], v[180:195]
	ds_read_b64_tr_b16 v[230:231], v159 offset:41984
	ds_read_b64_tr_b16 v[232:233], v159 offset:42496
	v_exp_f32_e32 v74, v74
	v_exp_f32_e32 v75, v75
	v_add_f32_e32 v157, v157, v74
	v_add_f32_e32 v157, v157, v75
	v_cvt_pk_bf16_f32 v69, v74, v75
	s_waitcnt lgkmcnt(15)
	v_mfma_f32_32x32x16_bf16 v[238:253], v[234:237], v[88:91], v[238:253]
	ds_read_b64_tr_b16 v[234:235], v159 offset:43008
	ds_read_b64_tr_b16 v[236:237], v159 offset:43520
	v_exp_f32_e32 v76, v76
	v_exp_f32_e32 v77, v77
	v_add_f32_e32 v156, v156, v76
	v_add_f32_e32 v156, v156, v77
	v_cvt_pk_bf16_f32 v70, v76, v77
	s_waitcnt lgkmcnt(15)
	v_mfma_f32_32x32x16_bf16 v[180:195], v[164:167], v[88:91], v[180:195]
	ds_read_b64_tr_b16 v[164:165], v159 offset:44032
	ds_read_b64_tr_b16 v[166:167], v159 offset:44544
	v_exp_f32_e32 v78, v78
	v_exp_f32_e32 v79, v79
	v_add_f32_e32 v157, v157, v78
	v_add_f32_e32 v157, v157, v79
	v_cvt_pk_bf16_f32 v71, v78, v79
	s_waitcnt lgkmcnt(15)
	v_mfma_f32_32x32x16_bf16 v[238:253], v[168:171], v[84:87], v[238:253]
	v_exp_f32_e32 v48, v48
	v_exp_f32_e32 v49, v49
	v_add_f32_e32 v156, v156, v48
	v_add_f32_e32 v156, v156, v49
	v_cvt_pk_bf16_f32 v48, v48, v49
	s_waitcnt lgkmcnt(15)
	v_mfma_f32_32x32x16_bf16 v[180:195], v[172:175], v[84:87], v[180:195]
	v_exp_f32_e32 v50, v50
	v_exp_f32_e32 v51, v51
	v_add_f32_e32 v157, v157, v50
	v_add_f32_e32 v157, v157, v51
	v_cvt_pk_bf16_f32 v49, v50, v51
	s_waitcnt lgkmcnt(15)
	v_mfma_f32_32x32x16_bf16 v[238:253], v[148:151], v[80:83], v[238:253]
	v_exp_f32_e32 v52, v52
	v_exp_f32_e32 v53, v53
	v_add_f32_e32 v156, v156, v52
	v_add_f32_e32 v156, v156, v53
	v_cvt_pk_bf16_f32 v50, v52, v53
	s_waitcnt lgkmcnt(15)
	v_mfma_f32_32x32x16_bf16 v[180:195], v[152:155], v[80:83], v[180:195]
	v_exp_f32_e32 v54, v54
	v_exp_f32_e32 v55, v55
	v_add_f32_e32 v157, v157, v54
	v_add_f32_e32 v157, v157, v55
	v_cvt_pk_bf16_f32 v51, v54, v55
	s_nop 1
	s_waitcnt lgkmcnt(0)
	v_mfma_f32_32x32x16_bf16 v[16:31], v[64:67], v[196:199], v[16:31]
	v_exp_f32_e32 v56, v56
	v_exp_f32_e32 v57, v57
	v_add_f32_e32 v156, v156, v56
	v_add_f32_e32 v156, v156, v57
	v_cvt_pk_bf16_f32 v52, v56, v57
	s_nop 1
	v_mfma_f32_32x32x16_bf16 v[32:47], v[64:67], v[212:215], v[32:47]
	s_mul_i32 s53, s48, 0x3000
	s_add_i32 s4, s52, 2
	s_cmp_ge_u32 s4, s86
	s_cbranch_scc1 .Lat_u1x_nodma
	s_add_i32 s4, s53, 0xffffd000
	s_cmp_lg_u32 s48, 0
	s_cselect_b32 s4, s4, 0x6000
	s_add_i32 s5, s4, s97
	s_mov_b32 m0, s5
	s_add_i32 s4, s4, s72
	global_load_lds_dwordx4 v[126:127], off
	s_mov_b32 m0, s4
	s_cmp_lt_u32 s69, 4
	s_cbranch_scc0 .Lat_u1x_nok2
	global_load_lds_dwordx4 v[14:15], off
.Lat_u1x_nok2:
	s_lshl_b32 s5, s50, 13
	s_xor_b32 s5, s5, 0x4000
	s_add_i32 s5, s5, s73
	s_mov_b32 m0, s5
	s_nop 0
	global_load_lds_dwordx4 v[124:125], off

; #define WAIT_BAR(N) asm volatile("s_waitcnt vmcnt(" #N ") lgkmcnt(0)\n\ts_barrier" ::: "memory")
; #define DMA_TILE(t, ks, vs) do { glds16(ksrc + (long)(t) * KVBLK * KNP, (unsigned)__builtin_amdgcn_readfirstlane(kdst + (ks) * KSLOT)); \
;         glds16(k2src + (long)(t) * KVBLK * KPP, (unsigned)__builtin_amdgcn_readfirstlane(k2dst + (ks) * KSLOT)); \
;         glds16(vsrc + (long)(t) * KVBLK * VP, (unsigned)__builtin_amdgcn_readfirstlane(vdst + (vs) * VSLOT)); } while (0)
; #define K_LOAD(ks) do { const LAS char* kp_ = kp0 + (ks) * KSLOT; \
;         _Pragma("unroll") for (int i_ = 0; i_ < 6; ++i_) { kf[2 * i_] = *(const LAS bf16x8*)(kp_ + i_ * 2048); kf[2 * i_ + 1] = *(const LAS bf16x8*)(kp_ + i_ * 2048 + 512); } SBAR(); } while (0)
; __device__ __forceinline__ void attn_unit(int b, int h, int qb, const bf16* Q, const bf16* __restrict__ Kn, const bf16* __restrict__ Kpe, const bf16* __restrict__ V, bf16* O, float* ASS, LAS char* shm) {
;     ...
;         for (int t = 0; t < NT; ++t) {
;             if (t + 1 < NT) { WAIT_BAR(3); } else { WAIT_BAR(0); }
;             K_LOAD(ks);
;             if (t + 2 < NT) DMA_TILE(t + 2, (ks == 0) ? 2 : ks - 1, (vs + 2) & 3);
;     ...
;         for (int t = 0; t < NT; ++t) {
;             if (t + 1 < NT) { WAIT_BAR(3); } else { WAIT_BAR(0); }
.Lat_u1x_end:
	s_cmp_eq_u32 s52, s86
	s_cbranch_scc1 .Lat_u1_tail
	s_add_i32 s4, s52, 1
	s_cmp_ge_u32 s4, s86
	s_cbranch_scc1 .Lat_u1y_lw
	s_cmp_lt_u32 s69, 4
	s_cbranch_scc0 .Lat_u1y_w2
	s_waitcnt vmcnt(3) lgkmcnt(0)
	s_branch .Lat_u1y_bar

.Lat_u1y_bar:
	s_barrier
	s_lshr_b32 s4, s69, 1
	s_sub_u32 s4, s52, s4
	s_cmp_gt_i32 s4, s87
	s_cbranch_scc1 .Lat_u1y_noqk
	s_mul_i32 s53, s48, 0x3000
	v_add_u32_e32 v158, s53, v146
	ds_read_b128 v[196:199], v158
	ds_read_b128 v[200:203], v158 offset:512
	ds_read_b128 v[204:207], v158 offset:2048
	ds_read_b128 v[208:211], v158 offset:2560
	ds_read_b128 v[212:215], v158 offset:4096
	ds_read_b128 v[230:233], v158 offset:4608
	ds_read_b128 v[234:237], v158 offset:6144
	ds_read_b128 v[164:167], v158 offset:6656
	ds_read_b128 v[168:171], v158 offset:8192
	ds_read_b128 v[172:175], v158 offset:8704
	ds_read_b128 v[148:151], v158 offset:10240
	ds_read_b128 v[152:155], v158 offset:10752
	s_lshl_b32 s4, s50, 13
	s_add_i32 s4, s4, 0x6000
	s_and_b32 s4, s4, 0x6000
	v_add_u32_e32 v159, s4, v144
	v_mov_b32_e32 v156, 0
	v_mov_b32_e32 v157, 0
	s_waitcnt lgkmcnt(11)
	v_mfma_f32_32x32x16_bf16 v[64:79], v[196:199], v[100:103], v[104:119]
	ds_read_b64_tr_b16 v[196:197], v159 offset:36864
	ds_read_b64_tr_b16 v[198:199], v159 offset:37376
	v_exp_f32_e32 v238, v238
	v_exp_f32_e32 v239, v239
	v_add_f32_e32 v156, v156, v238
	v_add_f32_e32 v156, v156, v239
	v_cvt_pk_bf16_f32 v238, v238, v239
	s_waitcnt lgkmcnt(12)
	v_mfma_f32_32x32x16_bf16 v[48:63], v[200:203], v[100:103], v[104:119]
	ds_read_b64_tr_b16 v[200:201], v159 offset:37888
	ds_read_b64_tr_b16 v[202:203], v159 offset:38400
	v_exp_f32_e32 v240, v240
	v_exp_f32_e32 v241, v241
	v_add_f32_e32 v157, v157, v240
	v_add_f32_e32 v157, v157, v241
	v_cvt_pk_bf16_f32 v239, v240, v241
	s_waitcnt lgkmcnt(13)
	v_mfma_f32_32x32x16_bf16 v[64:79], v[204:207], v[96:99], v[64:79]
	ds_read_b64_tr_b16 v[204:205], v159 offset:38912
	ds_read_b64_tr_b16 v[206:207], v159 offset:39424
	v_exp_f32_e32 v242, v242
	v_exp_f32_e32 v243, v243
	v_add_f32_e32 v156, v156, v242
	v_add_f32_e32 v156, v156, v243
	v_cvt_pk_bf16_f32 v240, v242, v243
	s_waitcnt lgkmcnt(14)
	v_mfma_f32_32x32x16_bf16 v[48:63], v[208:211], v[96:99], v[48:63]
	ds_read_b64_tr_b16 v[208:209], v159 offset:39936
	ds_read_b64_tr_b16 v[210:211], v159 offset:40448
	v_exp_f32_e32 v244, v244
	v_exp_f32_e32 v245, v245
	v_add_f32_e32 v157, v157, v244
	v_add_f32_e32 v157, v157, v245
	v_cvt_pk_bf16_f32 v241, v244, v245
	s_waitcnt lgkmcnt(15)
	v_mfma_f32_32x32x16_bf16 v[64:79], v[212:215], v[92:95], v[64:79]
	ds_read_b64_tr_b16 v[212:213], v159 offset:40960
	ds_read_b64_tr_b16 v[214:215], v159 offset:41472
	v_exp_f32_e32 v246, v246
	v_exp_f32_e32 v247, v247
	v_add_f32_e32 v156, v156, v246
	v_add_f32_e32 v156, v156, v247
	v_cvt_pk_bf16_f32 v242, v246, v247
	s_waitcnt lgkmcnt(15)
	v_mfma_f32_32x32x16_bf16 v[48:63], v[230:233], v[92:95], v[48:63]
	ds_read_b64_tr_b16 v[230:231], v159 offset:41984
	ds_read_b64_tr_b16 v[232:233], v159 offset:42496
	v_exp_f32_e32 v248, v248
	v_exp_f32_e32 v249, v249
	v_add_f32_e32 v157, v157, v248
	v_add_f32_e32 v157, v157, v249
	v_cvt_pk_bf16_f32 v243, v248, v249
	s_waitcnt lgkmcnt(15)
	v_mfma_f32_32x32x16_bf16 v[64:79], v[234:237], v[88:91], v[64:79]
	ds_read_b64_tr_b16 v[234:235], v159 offset:43008
	ds_read_b64_tr_b16 v[236:237], v159 offset:43520
	v_exp_f32_e32 v250, v250
	v_exp_f32_e32 v251, v251
	v_add_f32_e32 v156, v156, v250
	v_add_f32_e32 v156, v156, v251
	v_cvt_pk_bf16_f32 v244, v250, v251
	s_waitcnt lgkmcnt(15)
	v_mfma_f32_32x32x16_bf16 v[48:63], v[164:167], v[88:91], v[48:63]
	ds_read_b64_tr_b16 v[164:165], v159 offset:44032
	ds_read_b64_tr_b16 v[166:167], v159 offset:44544
	v_exp_f32_e32 v252, v252
	v_exp_f32_e32 v253, v253
	v_add_f32_e32 v157, v157, v252
	v_add_f32_e32 v157, v157, v253
	v_cvt_pk_bf16_f32 v245, v252, v253
	s_waitcnt lgkmcnt(15)
	v_mfma_f32_32x32x16_bf16 v[64:79], v[168:171], v[84:87], v[64:79]
	v_exp_f32_e32 v180, v180
	v_exp_f32_e32 v181, v181
	v_add_f32_e32 v156, v156, v180
	v_add_f32_e32 v156, v156, v181
	v_cvt_pk_bf16_f32 v180, v180, v181
	s_waitcnt lgkmcnt(15)
	v_mfma_f32_32x32x16_bf16 v[48:63], v[172:175], v[84:87], v[48:63]
	v_exp_f32_e32 v182, v182
	v_exp_f32_e32 v183, v183
	v_add_f32_e32 v157, v157, v182
	v_add_f32_e32 v157, v157, v183
	v_cvt_pk_bf16_f32 v181, v182, v183
	s_waitcnt lgkmcnt(15)
	v_mfma_f32_32x32x16_bf16 v[64:79], v[148:151], v[80:83], v[64:79]
	v_exp_f32_e32 v184, v184
	v_exp_f32_e32 v185, v185
	v_add_f32_e32 v156, v156, v184
	v_add_f32_e32 v156, v156, v185
	v_cvt_pk_bf16_f32 v182, v184, v185
	s_waitcnt lgkmcnt(15)
	v_mfma_f32_32x32x16_bf16 v[48:63], v[152:155], v[80:83], v[48:63]
	v_exp_f32_e32 v186, v186
	v_exp_f32_e32 v187, v187
	v_add_f32_e32 v157, v157, v186
	v_add_f32_e32 v157, v157, v187
	v_cvt_pk_bf16_f32 v183, v186, v187
	s_nop 1
	s_waitcnt lgkmcnt(0)
	v_mfma_f32_32x32x16_bf16 v[16:31], v[238:241], v[196:199], v[16:31]
	v_exp_f32_e32 v188, v188
	v_exp_f32_e32 v189, v189
	v_add_f32_e32 v156, v156, v188
	v_add_f32_e32 v156, v156, v189
	v_cvt_pk_bf16_f32 v184, v188, v189
	s_nop 1
	v_mfma_f32_32x32x16_bf16 v[32:47], v[238:241], v[212:215], v[32:47]
	s_mul_i32 s53, s48, 0x3000
	s_add_i32 s4, s52, 2
	s_cmp_ge_u32 s4, s86
	s_cbranch_scc1 .Lat_u1y_nodma
	s_add_i32 s4, s53, 0xffffd000
	s_cmp_lg_u32 s48, 0
	s_cselect_b32 s4, s4, 0x6000
	s_add_i32 s5, s4, s97
	s_mov_b32 m0, s5
	s_add_i32 s4, s4, s72
	global_load_lds_dwordx4 v[126:127], off
	s_mov_b32 m0, s4
	s_cmp_lt_u32 s69, 4
	s_cbranch_scc0 .Lat_u1y_nok2
	global_load_lds_dwordx4 v[14:15], off

; #define SBAR() __builtin_amdgcn_sched_barrier(0)
; #define WAIT_BAR(N) asm volatile("s_waitcnt vmcnt(" #N ") lgkmcnt(0)\n\ts_barrier" ::: "memory")
; #define DMA_TILE(t, ks, vs) do { glds16(ksrc + (long)(t) * KVBLK * KNP, (unsigned)__builtin_amdgcn_readfirstlane(kdst + (ks) * KSLOT)); \
;         glds16(k2src + (long)(t) * KVBLK * KPP, (unsigned)__builtin_amdgcn_readfirstlane(k2dst + (ks) * KSLOT)); \
;         glds16(vsrc + (long)(t) * KVBLK * VP, (unsigned)__builtin_amdgcn_readfirstlane(vdst + (vs) * VSLOT)); } while (0)
; #define V_LOAD(vs) do { const LAS char* vp_ = vp0 + (vs) * VSLOT; \
;         _Pragma("unroll") for (int i_ = 0; i_ < 8; ++i_) { vlo[i_] = vtr(vp_ + ((i_ >> 2) * 4096 + (i_ & 3) * 1024)); vhi[i_] = vtr(vp_ + ((i_ >> 2) * 4096 + (i_ & 3) * 1024 + 512)); } SBAR(); } while (0)
; __device__ __forceinline__ void attn_unit(int b, int h, int qb, const bf16* Q, const bf16* __restrict__ Kn, const bf16* __restrict__ Kpe, const bf16* __restrict__ V, bf16* O, float* ASS, LAS char* shm) {
;     ...
;         for (int t = 0; t < NT; ++t) {
;             if (t + 1 < NT) { WAIT_BAR(3); } else { WAIT_BAR(0); }
;             if (t > 0) V_LOAD((vs + 3) & 3);
;             if (t + 2 < NT) DMA_TILE(t + 2, (ks == 0) ? 2 : ks - 1, (vs + 2) & 3);
;             SBAR();
.Lat_u1x_idle:
	s_mul_i32 s53, s48, 0x3000
	s_add_i32 s4, s52, 2
	s_cmp_ge_u32 s4, s86
	s_cbranch_scc1 .Lat_u1xn_nodma
	s_add_i32 s4, s53, 0xffffd000
	s_cmp_lg_u32 s48, 0
	s_cselect_b32 s4, s4, 0x6000
	s_add_i32 s5, s4, s97
	s_mov_b32 m0, s5
	s_add_i32 s4, s4, s72
	global_load_lds_dwordx4 v[126:127], off
	s_mov_b32 m0, s4
	s_cmp_lt_u32 s69, 4
	s_cbranch_scc0 .Lat_u1xn_nok2
	global_load_lds_dwordx4 v[14:15], off

; #define WAIT_BAR(N) asm volatile("s_waitcnt vmcnt(" #N ") lgkmcnt(0)\n\ts_barrier" ::: "memory")
; #define DMA_TILE(t, ks, vs) do { glds16(ksrc + (long)(t) * KVBLK * KNP, (unsigned)__builtin_amdgcn_readfirstlane(kdst + (ks) * KSLOT)); \
;         glds16(k2src + (long)(t) * KVBLK * KPP, (unsigned)__builtin_amdgcn_readfirstlane(k2dst + (ks) * KSLOT)); \
;         glds16(vsrc + (long)(t) * KVBLK * VP, (unsigned)__builtin_amdgcn_readfirstlane(vdst + (vs) * VSLOT)); } while (0)
; #define K_LOAD(ks) do { const LAS char* kp_ = kp0 + (ks) * KSLOT; \
;         _Pragma("unroll") for (int i_ = 0; i_ < 6; ++i_) { kf[2 * i_] = *(const LAS bf16x8*)(kp_ + i_ * 2048); kf[2 * i_ + 1] = *(const LAS bf16x8*)(kp_ + i_ * 2048 + 512); } SBAR(); } while (0)
; __device__ __forceinline__ void attn_unit(int b, int h, int qb, const bf16* Q, const bf16* __restrict__ Kn, const bf16* __restrict__ Kpe, const bf16* __restrict__ V, bf16* O, float* ASS, LAS char* shm) {
;     ...
;     int ks = 0, vs = 0;
;     if (wid < 4) {
;         for (int t = 0; t < NT; ++t) {
;             if (t + 1 < NT) { WAIT_BAR(3); } else { WAIT_BAR(0); }
;             K_LOAD(ks);
;             if (t + 2 < NT) DMA_TILE(t + 2, (ks == 0) ? 2 : ks - 1, (vs + 2) & 3);
;     ...
;         for (int t = 0; t < NT; ++t) {
;             if (t + 1 < NT) { WAIT_BAR(3); } else { WAIT_BAR(0); }
.Lat_u2_loop:
	s_add_i32 s4, s62, 1
	s_cmp_ge_u32 s4, s90
	s_cbranch_scc1 .Lat_u2x_lw
	s_cmp_lt_u32 s56, 4
	s_cbranch_scc0 .Lat_u2x_w2
	s_waitcnt vmcnt(3) lgkmcnt(0)
	s_branch .Lat_u2x_bar

.Lat_u2x_bar:
	s_barrier
	s_lshr_b32 s4, s56, 1
	s_sub_u32 s4, s62, s4
	s_cmp_gt_i32 s4, s91
	s_cbranch_scc1 .Lat_u2x_noqk
	s_mul_i32 s63, s61, 0x3000
	v_add_u32_e32 v158, s63, v146
	ds_read_b128 v[196:199], v158
	ds_read_b128 v[200:203], v158 offset:512
	ds_read_b128 v[204:207], v158 offset:2048
	ds_read_b128 v[208:211], v158 offset:2560
	ds_read_b128 v[212:215], v158 offset:4096
	ds_read_b128 v[230:233], v158 offset:4608
	ds_read_b128 v[234:237], v158 offset:6144
	ds_read_b128 v[164:167], v158 offset:6656
	ds_read_b128 v[168:171], v158 offset:8192
	ds_read_b128 v[172:175], v158 offset:8704
	ds_read_b128 v[148:151], v158 offset:10240
	ds_read_b128 v[152:155], v158 offset:10752
	s_lshl_b32 s4, s64, 13
	s_add_i32 s4, s4, 0x6000
	s_and_b32 s4, s4, 0x6000
	v_add_u32_e32 v159, s4, v143
	v_mov_b32_e32 v156, 0
	v_mov_b32_e32 v157, 0
	s_waitcnt lgkmcnt(11)
	v_mfma_f32_32x32x16_bf16 v[238:253], v[196:199], v[86:89], v[104:119]
	ds_read_b64_tr_b16 v[196:197], v159 offset:36864
	ds_read_b64_tr_b16 v[198:199], v159 offset:37376
	v_exp_f32_e32 v50, v50
	v_exp_f32_e32 v51, v51
	v_add_f32_e32 v156, v156, v50
	v_add_f32_e32 v156, v156, v51
	v_cvt_pk_bf16_f32 v50, v50, v51
	s_waitcnt lgkmcnt(12)
	v_mfma_f32_32x32x16_bf16 v[180:195], v[200:203], v[86:89], v[104:119]
	ds_read_b64_tr_b16 v[200:201], v159 offset:37888
	ds_read_b64_tr_b16 v[202:203], v159 offset:38400
	v_exp_f32_e32 v52, v52
	v_exp_f32_e32 v53, v53
	v_add_f32_e32 v157, v157, v52
	v_add_f32_e32 v157, v157, v53
	v_cvt_pk_bf16_f32 v51, v52, v53
	s_waitcnt lgkmcnt(13)
	v_mfma_f32_32x32x16_bf16 v[238:253], v[204:207], v[82:85], v[238:253]
	ds_read_b64_tr_b16 v[204:205], v159 offset:38912
	ds_read_b64_tr_b16 v[206:207], v159 offset:39424
	v_exp_f32_e32 v54, v54
	v_exp_f32_e32 v55, v55
	v_add_f32_e32 v156, v156, v54
	v_add_f32_e32 v156, v156, v55
	v_cvt_pk_bf16_f32 v52, v54, v55
	s_waitcnt lgkmcnt(14)
	v_mfma_f32_32x32x16_bf16 v[180:195], v[208:211], v[82:85], v[180:195]
	ds_read_b64_tr_b16 v[208:209], v159 offset:39936
	ds_read_b64_tr_b16 v[210:211], v159 offset:40448
	v_exp_f32_e32 v56, v56
	v_exp_f32_e32 v57, v57
	v_add_f32_e32 v157, v157, v56
	v_add_f32_e32 v157, v157, v57
	v_cvt_pk_bf16_f32 v53, v56, v57
	s_waitcnt lgkmcnt(15)
	v_mfma_f32_32x32x16_bf16 v[238:253], v[212:215], v[78:81], v[238:253]
	ds_read_b64_tr_b16 v[212:213], v159 offset:40960
	ds_read_b64_tr_b16 v[214:215], v159 offset:41472
	v_exp_f32_e32 v58, v58
	v_exp_f32_e32 v59, v59
	v_add_f32_e32 v156, v156, v58
	v_add_f32_e32 v156, v156, v59
	v_cvt_pk_bf16_f32 v54, v58, v59
	s_waitcnt lgkmcnt(15)
	v_mfma_f32_32x32x16_bf16 v[180:195], v[230:233], v[78:81], v[180:195]
	ds_read_b64_tr_b16 v[230:231], v159 offset:41984
	ds_read_b64_tr_b16 v[232:233], v159 offset:42496
	v_exp_f32_e32 v60, v60
	v_exp_f32_e32 v61, v61
	v_add_f32_e32 v157, v157, v60
	v_add_f32_e32 v157, v157, v61
	v_cvt_pk_bf16_f32 v55, v60, v61
	s_waitcnt lgkmcnt(15)
	v_mfma_f32_32x32x16_bf16 v[238:253], v[234:237], v[74:77], v[238:253]
	ds_read_b64_tr_b16 v[234:235], v159 offset:43008
	ds_read_b64_tr_b16 v[236:237], v159 offset:43520
	v_exp_f32_e32 v62, v62
	v_exp_f32_e32 v63, v63
	v_add_f32_e32 v156, v156, v62
	v_add_f32_e32 v156, v156, v63
	v_cvt_pk_bf16_f32 v56, v62, v63
	s_waitcnt lgkmcnt(15)
	v_mfma_f32_32x32x16_bf16 v[180:195], v[164:167], v[74:77], v[180:195]
	ds_read_b64_tr_b16 v[164:165], v159 offset:44032
	ds_read_b64_tr_b16 v[166:167], v159 offset:44544
	v_exp_f32_e32 v64, v64
	v_exp_f32_e32 v65, v65
	v_add_f32_e32 v157, v157, v64
	v_add_f32_e32 v157, v157, v65
	v_cvt_pk_bf16_f32 v57, v64, v65
	s_waitcnt lgkmcnt(15)
	v_mfma_f32_32x32x16_bf16 v[238:253], v[168:171], v[70:73], v[238:253]
	v_exp_f32_e32 v34, v34
	v_exp_f32_e32 v35, v35
	v_add_f32_e32 v156, v156, v34
	v_add_f32_e32 v156, v156, v35
	v_cvt_pk_bf16_f32 v34, v34, v35
	s_waitcnt lgkmcnt(15)
	v_mfma_f32_32x32x16_bf16 v[180:195], v[172:175], v[70:73], v[180:195]
	v_exp_f32_e32 v36, v36
	v_exp_f32_e32 v37, v37
	v_add_f32_e32 v157, v157, v36
	v_add_f32_e32 v157, v157, v37
	v_cvt_pk_bf16_f32 v35, v36, v37
	s_waitcnt lgkmcnt(15)
	v_mfma_f32_32x32x16_bf16 v[238:253], v[148:151], v[66:69], v[238:253]
	v_exp_f32_e32 v38, v38
	v_exp_f32_e32 v39, v39
	v_add_f32_e32 v156, v156, v38
	v_add_f32_e32 v156, v156, v39
	v_cvt_pk_bf16_f32 v36, v38, v39
	s_waitcnt lgkmcnt(15)
	v_mfma_f32_32x32x16_bf16 v[180:195], v[152:155], v[66:69], v[180:195]
	v_exp_f32_e32 v40, v40
	v_exp_f32_e32 v41, v41
	v_add_f32_e32 v157, v157, v40
	v_add_f32_e32 v157, v157, v41
	v_cvt_pk_bf16_f32 v37, v40, v41
	s_nop 1
	s_waitcnt lgkmcnt(0)
	v_mfma_f32_32x32x16_bf16 v[18:33], v[50:53], v[196:199], v[18:33]
	v_exp_f32_e32 v42, v42
	v_exp_f32_e32 v43, v43
	v_add_f32_e32 v156, v156, v42
	v_add_f32_e32 v156, v156, v43
	v_cvt_pk_bf16_f32 v38, v42, v43
	s_nop 1
	v_mfma_f32_32x32x16_bf16 v[2:17], v[50:53], v[212:215], v[2:17]
	s_mul_i32 s63, s61, 0x3000
	s_add_i32 s4, s62, 2
	s_cmp_ge_u32 s4, s90
	s_cbranch_scc1 .Lat_u2x_nodma
	s_add_i32 s4, s63, 0xffffd000
	s_cmp_lg_u32 s61, 0
	s_cselect_b32 s4, s4, 0x6000
	s_add_i32 s5, s4, s58
	s_mov_b32 m0, s5
	s_add_i32 s4, s4, s59
	global_load_lds_dwordx4 v[126:127], off
	s_mov_b32 m0, s4
	s_cmp_lt_u32 s56, 4
	s_cbranch_scc0 .Lat_u2x_nok2
	global_load_lds_dwordx4 v[122:123], off
.Lat_u2x_nok2:
	s_lshl_b32 s5, s64, 13
	s_xor_b32 s5, s5, 0x4000
	s_add_i32 s5, s5, s60
	s_mov_b32 m0, s5
	s_nop 0
	global_load_lds_dwordx4 v[124:125], off

; #define WAIT_BAR(N) asm volatile("s_waitcnt vmcnt(" #N ") lgkmcnt(0)\n\ts_barrier" ::: "memory")
; #define DMA_TILE(t, ks, vs) do { glds16(ksrc + (long)(t) * KVBLK * KNP, (unsigned)__builtin_amdgcn_readfirstlane(kdst + (ks) * KSLOT)); \
;         glds16(k2src + (long)(t) * KVBLK * KPP, (unsigned)__builtin_amdgcn_readfirstlane(k2dst + (ks) * KSLOT)); \
;         glds16(vsrc + (long)(t) * KVBLK * VP, (unsigned)__builtin_amdgcn_readfirstlane(vdst + (vs) * VSLOT)); } while (0)
; #define K_LOAD(ks) do { const LAS char* kp_ = kp0 + (ks) * KSLOT; \
;         _Pragma("unroll") for (int i_ = 0; i_ < 6; ++i_) { kf[2 * i_] = *(const LAS bf16x8*)(kp_ + i_ * 2048); kf[2 * i_ + 1] = *(const LAS bf16x8*)(kp_ + i_ * 2048 + 512); } SBAR(); } while (0)
; __device__ __forceinline__ void attn_unit(int b, int h, int qb, const bf16* Q, const bf16* __restrict__ Kn, const bf16* __restrict__ Kpe, const bf16* __restrict__ V, bf16* O, float* ASS, LAS char* shm) {
;     ...
;         for (int t = 0; t < NT; ++t) {
;             if (t + 1 < NT) { WAIT_BAR(3); } else { WAIT_BAR(0); }
;             K_LOAD(ks);
;             if (t + 2 < NT) DMA_TILE(t + 2, (ks == 0) ? 2 : ks - 1, (vs + 2) & 3);
;     ...
;         for (int t = 0; t < NT; ++t) {
;             if (t + 1 < NT) { WAIT_BAR(3); } else { WAIT_BAR(0); }
.Lat_u2x_end:
	s_cmp_eq_u32 s62, s90
	s_cbranch_scc1 .Lat_u2_tail
	s_add_i32 s4, s62, 1
	s_cmp_ge_u32 s4, s90
	s_cbranch_scc1 .Lat_u2y_lw
	s_cmp_lt_u32 s56, 4
	s_cbranch_scc0 .Lat_u2y_w2
	s_waitcnt vmcnt(3) lgkmcnt(0)
	s_branch .Lat_u2y_bar

.Lat_u2y_bar:
	s_barrier
	s_lshr_b32 s4, s56, 1
	s_sub_u32 s4, s62, s4
	s_cmp_gt_i32 s4, s91
	s_cbranch_scc1 .Lat_u2y_noqk
	s_mul_i32 s63, s61, 0x3000
	v_add_u32_e32 v158, s63, v146
	ds_read_b128 v[196:199], v158
	ds_read_b128 v[200:203], v158 offset:512
	ds_read_b128 v[204:207], v158 offset:2048
	ds_read_b128 v[208:211], v158 offset:2560
	ds_read_b128 v[212:215], v158 offset:4096
	ds_read_b128 v[230:233], v158 offset:4608
	ds_read_b128 v[234:237], v158 offset:6144
	ds_read_b128 v[164:167], v158 offset:6656
	ds_read_b128 v[168:171], v158 offset:8192
	ds_read_b128 v[172:175], v158 offset:8704
	ds_read_b128 v[148:151], v158 offset:10240
	ds_read_b128 v[152:155], v158 offset:10752
	s_lshl_b32 s4, s64, 13
	s_add_i32 s4, s4, 0x6000
	s_and_b32 s4, s4, 0x6000
	v_add_u32_e32 v159, s4, v143
	v_mov_b32_e32 v156, 0
	v_mov_b32_e32 v157, 0
	s_waitcnt lgkmcnt(11)
	v_mfma_f32_32x32x16_bf16 v[50:65], v[196:199], v[86:89], v[104:119]
	ds_read_b64_tr_b16 v[196:197], v159 offset:36864
	ds_read_b64_tr_b16 v[198:199], v159 offset:37376
	v_exp_f32_e32 v238, v238
	v_exp_f32_e32 v239, v239
	v_add_f32_e32 v156, v156, v238
	v_add_f32_e32 v156, v156, v239
	v_cvt_pk_bf16_f32 v238, v238, v239
	s_waitcnt lgkmcnt(12)
	v_mfma_f32_32x32x16_bf16 v[34:49], v[200:203], v[86:89], v[104:119]
	ds_read_b64_tr_b16 v[200:201], v159 offset:37888
	ds_read_b64_tr_b16 v[202:203], v159 offset:38400
	v_exp_f32_e32 v240, v240
	v_exp_f32_e32 v241, v241
	v_add_f32_e32 v157, v157, v240
	v_add_f32_e32 v157, v157, v241
	v_cvt_pk_bf16_f32 v239, v240, v241
	s_waitcnt lgkmcnt(13)
	v_mfma_f32_32x32x16_bf16 v[50:65], v[204:207], v[82:85], v[50:65]
	ds_read_b64_tr_b16 v[204:205], v159 offset:38912
	ds_read_b64_tr_b16 v[206:207], v159 offset:39424
	v_exp_f32_e32 v242, v242
	v_exp_f32_e32 v243, v243
	v_add_f32_e32 v156, v156, v242
	v_add_f32_e32 v156, v156, v243
	v_cvt_pk_bf16_f32 v240, v242, v243
	s_waitcnt lgkmcnt(14)
	v_mfma_f32_32x32x16_bf16 v[34:49], v[208:211], v[82:85], v[34:49]
	ds_read_b64_tr_b16 v[208:209], v159 offset:39936
	ds_read_b64_tr_b16 v[210:211], v159 offset:40448
	v_exp_f32_e32 v244, v244
	v_exp_f32_e32 v245, v245
	v_add_f32_e32 v157, v157, v244
	v_add_f32_e32 v157, v157, v245
	v_cvt_pk_bf16_f32 v241, v244, v245
	s_waitcnt lgkmcnt(15)
	v_mfma_f32_32x32x16_bf16 v[50:65], v[212:215], v[78:81], v[50:65]
	ds_read_b64_tr_b16 v[212:213], v159 offset:40960
	ds_read_b64_tr_b16 v[214:215], v159 offset:41472
	v_exp_f32_e32 v246, v246
	v_exp_f32_e32 v247, v247
	v_add_f32_e32 v156, v156, v246
	v_add_f32_e32 v156, v156, v247
	v_cvt_pk_bf16_f32 v242, v246, v247
	s_waitcnt lgkmcnt(15)
	v_mfma_f32_32x32x16_bf16 v[34:49], v[230:233], v[78:81], v[34:49]
	ds_read_b64_tr_b16 v[230:231], v159 offset:41984
	ds_read_b64_tr_b16 v[232:233], v159 offset:42496
	v_exp_f32_e32 v248, v248
	v_exp_f32_e32 v249, v249
	v_add_f32_e32 v157, v157, v248
	v_add_f32_e32 v157, v157, v249
	v_cvt_pk_bf16_f32 v243, v248, v249
	s_waitcnt lgkmcnt(15)
	v_mfma_f32_32x32x16_bf16 v[50:65], v[234:237], v[74:77], v[50:65]
	ds_read_b64_tr_b16 v[234:235], v159 offset:43008
	ds_read_b64_tr_b16 v[236:237], v159 offset:43520
	v_exp_f32_e32 v250, v250
	v_exp_f32_e32 v251, v251
	v_add_f32_e32 v156, v156, v250
	v_add_f32_e32 v156, v156, v251
	v_cvt_pk_bf16_f32 v244, v250, v251
	s_waitcnt lgkmcnt(15)
	v_mfma_f32_32x32x16_bf16 v[34:49], v[164:167], v[74:77], v[34:49]
	ds_read_b64_tr_b16 v[164:165], v159 offset:44032
	ds_read_b64_tr_b16 v[166:167], v159 offset:44544
	v_exp_f32_e32 v252, v252
	v_exp_f32_e32 v253, v253
	v_add_f32_e32 v157, v157, v252
	v_add_f32_e32 v157, v157, v253
	v_cvt_pk_bf16_f32 v245, v252, v253
	s_waitcnt lgkmcnt(15)
	v_mfma_f32_32x32x16_bf16 v[50:65], v[168:171], v[70:73], v[50:65]
	v_exp_f32_e32 v180, v180
	v_exp_f32_e32 v181, v181
	v_add_f32_e32 v156, v156, v180
	v_add_f32_e32 v156, v156, v181
	v_cvt_pk_bf16_f32 v180, v180, v181
	s_waitcnt lgkmcnt(15)
	v_mfma_f32_32x32x16_bf16 v[34:49], v[172:175], v[70:73], v[34:49]
	v_exp_f32_e32 v182, v182
	v_exp_f32_e32 v183, v183
	v_add_f32_e32 v157, v157, v182
	v_add_f32_e32 v157, v157, v183
	v_cvt_pk_bf16_f32 v181, v182, v183
	s_waitcnt lgkmcnt(15)
	v_mfma_f32_32x32x16_bf16 v[50:65], v[148:151], v[66:69], v[50:65]
	v_exp_f32_e32 v184, v184
	v_exp_f32_e32 v185, v185
	v_add_f32_e32 v156, v156, v184
	v_add_f32_e32 v156, v156, v185
	v_cvt_pk_bf16_f32 v182, v184, v185
	s_waitcnt lgkmcnt(15)
	v_mfma_f32_32x32x16_bf16 v[34:49], v[152:155], v[66:69], v[34:49]
	v_exp_f32_e32 v186, v186
	v_exp_f32_e32 v187, v187
	v_add_f32_e32 v157, v157, v186
	v_add_f32_e32 v157, v157, v187
	v_cvt_pk_bf16_f32 v183, v186, v187
	s_nop 1
	s_waitcnt lgkmcnt(0)
	v_mfma_f32_32x32x16_bf16 v[18:33], v[238:241], v[196:199], v[18:33]
	v_exp_f32_e32 v188, v188
	v_exp_f32_e32 v189, v189
	v_add_f32_e32 v156, v156, v188
	v_add_f32_e32 v156, v156, v189
	v_cvt_pk_bf16_f32 v184, v188, v189
	s_nop 1
	v_mfma_f32_32x32x16_bf16 v[2:17], v[238:241], v[212:215], v[2:17]
	s_mul_i32 s63, s61, 0x3000
	s_add_i32 s4, s62, 2
	s_cmp_ge_u32 s4, s90
	s_cbranch_scc1 .Lat_u2y_nodma
	s_add_i32 s4, s63, 0xffffd000
	s_cmp_lg_u32 s61, 0
	s_cselect_b32 s4, s4, 0x6000
	s_add_i32 s5, s4, s58
	s_mov_b32 m0, s5
	s_add_i32 s4, s4, s59
	global_load_lds_dwordx4 v[126:127], off
	s_mov_b32 m0, s4
	s_cmp_lt_u32 s56, 4
	s_cbranch_scc0 .Lat_u2y_nok2
	global_load_lds_dwordx4 v[122:123], off

; #define SBAR() __builtin_amdgcn_sched_barrier(0)
; #define WAIT_BAR(N) asm volatile("s_waitcnt vmcnt(" #N ") lgkmcnt(0)\n\ts_barrier" ::: "memory")
; #define DMA_TILE(t, ks, vs) do { glds16(ksrc + (long)(t) * KVBLK * KNP, (unsigned)__builtin_amdgcn_readfirstlane(kdst + (ks) * KSLOT)); \
;         glds16(k2src + (long)(t) * KVBLK * KPP, (unsigned)__builtin_amdgcn_readfirstlane(k2dst + (ks) * KSLOT)); \
;         glds16(vsrc + (long)(t) * KVBLK * VP, (unsigned)__builtin_amdgcn_readfirstlane(vdst + (vs) * VSLOT)); } while (0)
; #define V_LOAD(vs) do { const LAS char* vp_ = vp0 + (vs) * VSLOT; \
;         _Pragma("unroll") for (int i_ = 0; i_ < 8; ++i_) { vlo[i_] = vtr(vp_ + ((i_ >> 2) * 4096 + (i_ & 3) * 1024)); vhi[i_] = vtr(vp_ + ((i_ >> 2) * 4096 + (i_ & 3) * 1024 + 512)); } SBAR(); } while (0)
; __device__ __forceinline__ void attn_unit(int b, int h, int qb, const bf16* Q, const bf16* __restrict__ Kn, const bf16* __restrict__ Kpe, const bf16* __restrict__ V, bf16* O, float* ASS, LAS char* shm) {
;     ...
;         for (int t = 0; t < NT; ++t) {
;             if (t + 1 < NT) { WAIT_BAR(3); } else { WAIT_BAR(0); }
;             if (t > 0) V_LOAD((vs + 3) & 3);
;             if (t + 2 < NT) DMA_TILE(t + 2, (ks == 0) ? 2 : ks - 1, (vs + 2) & 3);
;             SBAR();
.Lat_u2x_idle:
	s_mul_i32 s63, s61, 0x3000
	s_add_i32 s4, s62, 2
	s_cmp_ge_u32 s4, s90
	s_cbranch_scc1 .Lat_u2xn_nodma
	s_add_i32 s4, s63, 0xffffd000
	s_cmp_lg_u32 s61, 0
	s_cselect_b32 s4, s4, 0x6000
	s_add_i32 s5, s4, s58
	s_mov_b32 m0, s5
	s_add_i32 s4, s4, s59
	global_load_lds_dwordx4 v[126:127], off
	s_mov_b32 m0, s4
	s_cmp_lt_u32 s56, 4
	s_cbranch_scc0 .Lat_u2xn_nok2
	global_load_lds_dwordx4 v[122:123], off
